# out-projection (C/D half) epilogue software-pipelined: residual loads issued 14 ahead behind counted vmcnt, in-place add, store
# speedup vs baseline: 1.0085x; 1.0085x over previous
;     __device__ __forceinline__ void operator()(const f32x4 (&acc)[2][2][4][2], const Unit& u, int wr, int wc, int fr, int fq) const {
;     ...
;                 const int row = u.pm * BM + ai * HALF + wr * 64 + m * 16 + fr;
;                 const size_t off = (size_t)row * 1024 + col0;
;                 float ss = 0.f;
; #pragma unroll
;                 for (int bj = 0; bj < 2; ++bj)
; #pragma unroll
;                     for (int n = 0; n < 2; ++n) {
;                         const f32x4 o = *(const f32x4*)(res + off + bj * HALF + n * 16) + acc[ai][bj][m][n];
;                         *(f32x4*)(out + off + bj * HALF + n * 16) = o;
.LBB0_449:
	v_lshl_add_u32 v138, s41, 8, v140
	v_lshl_or_b32 v136, s40, 8, v142
	v_ashrrev_i32_e32 v139, 31, v138
	v_ashrrev_i32_e32 v137, 31, v136
	v_lshlrev_b64 v[144:145], 10, v[138:139]
	v_lshl_add_u64 v[144:145], v[144:145], 0, v[136:137]
	v_lshlrev_b64 v[148:149], 2, v[144:145]
	s_andn2_b64 vcc, exec, s[0:1]
	s_mov_b64 s[0:1], -1
	s_waitcnt lgkmcnt(0)
	v_mov_b32_e32 v136, v148
	v_add_u32_e32 v137, 0x10000, v148
	v_add_u32_e32 v138, 0x20000, v148
	v_add_u32_e32 v139, 0x30000, v148
	v_add_u32_e32 v144, 0x80000, v148
	v_add_u32_e32 v145, 0x90000, v148
	v_add_u32_e32 v146, 0xa0000, v148
	v_add_u32_e32 v147, 0xb0000, v148
	global_load_dwordx4 v[148:151], v136, s[4:5]
	global_load_dwordx4 v[152:155], v136, s[4:5] offset:64
	global_load_dwordx4 v[156:159], v136, s[4:5] offset:512
	global_load_dwordx4 v[160:163], v136, s[4:5] offset:576
	global_load_dwordx4 v[164:167], v137, s[4:5]
	global_load_dwordx4 v[168:171], v137, s[4:5] offset:64
	global_load_dwordx4 v[172:175], v137, s[4:5] offset:512
	global_load_dwordx4 v[176:179], v137, s[4:5] offset:576
	global_load_dwordx4 v[180:183], v138, s[4:5]
	global_load_dwordx4 v[184:187], v138, s[4:5] offset:64
	global_load_dwordx4 v[188:191], v138, s[4:5] offset:512
	global_load_dwordx4 v[206:209], v138, s[4:5] offset:576
	global_load_dwordx4 v[222:225], v139, s[4:5]
	global_load_dwordx4 v[226:229], v139, s[4:5] offset:64
	s_waitcnt vmcnt(13)
	v_pk_add_f32 v[128:129], v[128:129], v[150:151]
	v_pk_add_f32 v[126:127], v[126:127], v[148:149]
	global_store_dwordx4 v136, v[126:129], s[10:11]
	s_nop 0
	global_load_dwordx4 v[148:151], v139, s[4:5] offset:512
	s_waitcnt vmcnt(14)
	v_pk_add_f32 v[124:125], v[124:125], v[154:155]
	v_pk_add_f32 v[122:123], v[122:123], v[152:153]
	global_store_dwordx4 v136, v[122:125], s[10:11] offset:64
	s_nop 0
	global_load_dwordx4 v[152:155], v139, s[4:5] offset:576
	s_waitcnt vmcnt(15)
	v_pk_add_f32 v[120:121], v[120:121], v[158:159]
	v_pk_add_f32 v[118:119], v[118:119], v[156:157]
	global_store_dwordx4 v136, v[118:121], s[10:11] offset:512
	s_nop 0
	global_load_dwordx4 v[156:159], v144, s[4:5]
	s_waitcnt vmcnt(16)
	v_pk_add_f32 v[108:109], v[108:109], v[162:163]
	v_pk_add_f32 v[106:107], v[106:107], v[160:161]
	global_store_dwordx4 v136, v[106:109], s[10:11] offset:576
	s_nop 0
	global_load_dwordx4 v[160:163], v144, s[4:5] offset:64
	s_waitcnt vmcnt(17)
	v_pk_add_f32 v[116:117], v[116:117], v[166:167]
	v_pk_add_f32 v[114:115], v[114:115], v[164:165]
	global_store_dwordx4 v137, v[114:117], s[10:11]
	s_nop 0
	global_load_dwordx4 v[164:167], v144, s[4:5] offset:512
	s_waitcnt vmcnt(18)
	v_pk_add_f32 v[112:113], v[112:113], v[170:171]
	v_pk_add_f32 v[110:111], v[110:111], v[168:169]
	global_store_dwordx4 v137, v[110:113], s[10:11] offset:64
	s_nop 0
	global_load_dwordx4 v[168:171], v144, s[4:5] offset:576
	s_waitcnt vmcnt(19)
	v_pk_add_f32 v[104:105], v[104:105], v[174:175]
	v_pk_add_f32 v[102:103], v[102:103], v[172:173]
	global_store_dwordx4 v137, v[102:105], s[10:11] offset:512
	s_nop 0
	global_load_dwordx4 v[172:175], v145, s[4:5]
	s_waitcnt vmcnt(20)
	v_pk_add_f32 v[92:93], v[92:93], v[178:179]
	v_pk_add_f32 v[90:91], v[90:91], v[176:177]
	global_store_dwordx4 v137, v[90:93], s[10:11] offset:576
	s_nop 0
	global_load_dwordx4 v[176:179], v145, s[4:5] offset:64
	s_waitcnt vmcnt(21)
	v_pk_add_f32 v[100:101], v[100:101], v[182:183]
	v_pk_add_f32 v[98:99], v[98:99], v[180:181]
	global_store_dwordx4 v138, v[98:101], s[10:11]
	s_nop 0
	global_load_dwordx4 v[180:183], v145, s[4:5] offset:512
	s_waitcnt vmcnt(22)
	v_pk_add_f32 v[96:97], v[96:97], v[186:187]
	v_pk_add_f32 v[94:95], v[94:95], v[184:185]
	global_store_dwordx4 v138, v[94:97], s[10:11] offset:64
	s_nop 0
	global_load_dwordx4 v[184:187], v145, s[4:5] offset:576
	s_waitcnt vmcnt(23)
	v_pk_add_f32 v[88:89], v[88:89], v[190:191]
	v_pk_add_f32 v[86:87], v[86:87], v[188:189]
	global_store_dwordx4 v138, v[86:89], s[10:11] offset:512
	s_nop 0
	global_load_dwordx4 v[188:191], v146, s[4:5]
	s_waitcnt vmcnt(24)
;     __device__ __forceinline__ void operator()(const f32x4 (&acc)[2][2][4][2], const Unit& u, int wr, int wc, int fr, int fq) const {
;     ...
;                 const int row = u.pm * BM + ai * HALF + wr * 64 + m * 16 + fr;
;                 const size_t off = (size_t)row * 1024 + col0;
;                 float ss = 0.f;
; #pragma unroll
;                 for (int bj = 0; bj < 2; ++bj)
; #pragma unroll
;                     for (int n = 0; n < 2; ++n) {
;                         const f32x4 o = *(const f32x4*)(res + off + bj * HALF + n * 16) + acc[ai][bj][m][n];
;                         *(f32x4*)(out + off + bj * HALF + n * 16) = o;
	v_pk_add_f32 v[76:77], v[76:77], v[208:209]
	v_pk_add_f32 v[74:75], v[74:75], v[206:207]
	global_store_dwordx4 v138, v[74:77], s[10:11] offset:576
	s_nop 0
	global_load_dwordx4 v[206:209], v146, s[4:5] offset:64
	s_waitcnt vmcnt(25)
	v_pk_add_f32 v[84:85], v[84:85], v[224:225]
	v_pk_add_f32 v[82:83], v[82:83], v[222:223]
	global_store_dwordx4 v139, v[82:85], s[10:11]
	s_nop 0
	global_load_dwordx4 v[222:225], v146, s[4:5] offset:512
	s_waitcnt vmcnt(26)
	v_pk_add_f32 v[80:81], v[80:81], v[228:229]
	v_pk_add_f32 v[78:79], v[78:79], v[226:227]
	global_store_dwordx4 v139, v[78:81], s[10:11] offset:64
	s_nop 0
	global_load_dwordx4 v[226:229], v146, s[4:5] offset:576
	s_waitcnt vmcnt(26)
	v_pk_add_f32 v[72:73], v[72:73], v[150:151]
	v_pk_add_f32 v[70:71], v[70:71], v[148:149]
	global_store_dwordx4 v139, v[70:73], s[10:11] offset:512
	s_nop 0
	global_load_dwordx4 v[148:151], v147, s[4:5]
	s_waitcnt vmcnt(26)
	v_pk_add_f32 v[68:69], v[68:69], v[154:155]
	v_pk_add_f32 v[66:67], v[66:67], v[152:153]
	global_store_dwordx4 v139, v[66:69], s[10:11] offset:576
	s_nop 0
	global_load_dwordx4 v[152:155], v147, s[4:5] offset:64
	s_waitcnt vmcnt(26)
	v_pk_add_f32 v[64:65], v[64:65], v[158:159]
	v_pk_add_f32 v[62:63], v[62:63], v[156:157]
	global_store_dwordx4 v144, v[62:65], s[10:11]
	s_nop 0
	global_load_dwordx4 v[156:159], v147, s[4:5] offset:512
	s_waitcnt vmcnt(26)
	v_pk_add_f32 v[60:61], v[60:61], v[162:163]
	v_pk_add_f32 v[58:59], v[58:59], v[160:161]
	global_store_dwordx4 v144, v[58:61], s[10:11] offset:64
	s_nop 0
	global_load_dwordx4 v[160:163], v147, s[4:5] offset:576
	s_waitcnt vmcnt(26)
	v_pk_add_f32 v[56:57], v[56:57], v[166:167]
	v_pk_add_f32 v[54:55], v[54:55], v[164:165]
	global_store_dwordx4 v144, v[54:57], s[10:11] offset:512
	s_waitcnt vmcnt(25)
	v_pk_add_f32 v[44:45], v[44:45], v[170:171]
	v_pk_add_f32 v[42:43], v[42:43], v[168:169]
	global_store_dwordx4 v144, v[42:45], s[10:11] offset:576
	s_waitcnt vmcnt(24)
	v_pk_add_f32 v[52:53], v[52:53], v[174:175]
	v_pk_add_f32 v[50:51], v[50:51], v[172:173]
	global_store_dwordx4 v145, v[50:53], s[10:11]
	s_waitcnt vmcnt(23)
	v_pk_add_f32 v[48:49], v[48:49], v[178:179]
	v_pk_add_f32 v[46:47], v[46:47], v[176:177]
	global_store_dwordx4 v145, v[46:49], s[10:11] offset:64
	s_waitcnt vmcnt(22)
	v_pk_add_f32 v[40:41], v[40:41], v[182:183]
	v_pk_add_f32 v[38:39], v[38:39], v[180:181]
	global_store_dwordx4 v145, v[38:41], s[10:11] offset:512
	s_waitcnt vmcnt(21)
	v_pk_add_f32 v[28:29], v[28:29], v[186:187]
	v_pk_add_f32 v[26:27], v[26:27], v[184:185]
	global_store_dwordx4 v145, v[26:29], s[10:11] offset:576
	s_waitcnt vmcnt(20)
	v_pk_add_f32 v[36:37], v[36:37], v[190:191]
	v_pk_add_f32 v[34:35], v[34:35], v[188:189]
	global_store_dwordx4 v146, v[34:37], s[10:11]
	s_waitcnt vmcnt(19)
	v_pk_add_f32 v[32:33], v[32:33], v[208:209]
	v_pk_add_f32 v[30:31], v[30:31], v[206:207]
	global_store_dwordx4 v146, v[30:33], s[10:11] offset:64
	s_waitcnt vmcnt(18)
	v_pk_add_f32 v[24:25], v[24:25], v[224:225]
	v_pk_add_f32 v[22:23], v[22:23], v[222:223]
	global_store_dwordx4 v146, v[22:25], s[10:11] offset:512
	s_waitcnt vmcnt(17)
	v_pk_add_f32 v[12:13], v[12:13], v[228:229]
	v_pk_add_f32 v[10:11], v[10:11], v[226:227]
	global_store_dwordx4 v146, v[10:13], s[10:11] offset:576
	s_waitcnt vmcnt(16)
	v_pk_add_f32 v[20:21], v[20:21], v[150:151]
	v_pk_add_f32 v[18:19], v[18:19], v[148:149]
	global_store_dwordx4 v147, v[18:21], s[10:11]
	s_waitcnt vmcnt(15)
	v_pk_add_f32 v[16:17], v[16:17], v[154:155]
	v_pk_add_f32 v[14:15], v[14:15], v[152:153]
	global_store_dwordx4 v147, v[14:17], s[10:11] offset:64
	s_waitcnt vmcnt(14)
	v_pk_add_f32 v[8:9], v[8:9], v[158:159]
	v_pk_add_f32 v[6:7], v[6:7], v[156:157]
	global_store_dwordx4 v147, v[6:9], s[10:11] offset:512
	s_waitcnt vmcnt(13)
	v_pk_add_f32 v[4:5], v[4:5], v[162:163]
	v_pk_add_f32 v[2:3], v[2:3], v[160:161]
	global_store_dwordx4 v147, v[2:5], s[10:11] offset:576
	s_cbranch_vccnz .LBB0_438
	s_andn2_b64 vcc, exec, s[2:3]
	s_cbranch_vccnz .LBB0_437
	s_barrier
	s_branch .LBB0_437
